# adds to the previous version: three dead address computations removed from the phase B epilogue
# baseline (speedup 1.0000x reference)
; __device__ __forceinline__ unsigned cvt_pk_bf16(float lo, float hi) { f32x2 v = {lo, hi}; bf16x2_t b = __builtin_convertvector(v, bf16x2_t); return __builtin_bit_cast(unsigned, b); }
;     __device__ __forceinline__ void operator()(const f32x4 (&acc)[2][2][4][2], const Unit& u, int wr, int wc, int fr, int fq) const {
;     ...
;             for (int m = 0; m < 4; ++m) { const int r = row0 + ai * HALF + m * 16; const float s = rs ? rs[r] * cs : cs; bf16_t* rowp = Z + (size_t)r * ldc + col0;
;                 const int seq = r >> sshift, pos = r & ((1 << sshift) - 1), tile = pos >> 6, kv = pos & 63;
; #pragma unroll
;                 for (int bj = 0; bj < 2; ++bj) { const f32x4 v0 = acc[ai][bj][m][0] * s, v1 = acc[ai][bj][m][1] * s; u32x4 w;
;                     w.x = cvt_pk_bf16(v0[0], v0[1]); w.y = cvt_pk_bf16(v0[2], v0[3]); w.z = cvt_pk_bf16(v1[0], v1[1]); w.w = cvt_pk_bf16(v1[2], v1[3]);
.LBB0_102:
	v_or_b32_e32 v118, 16, v130
	v_ashrrev_i32_e32 v119, 31, v118
	v_mov_b64_e32 v[114:115], s[70:71]
	v_mad_i64_i32 v[114:115], s[26:27], v118, s35, v[114:115]
	s_and_b64 vcc, exec, s[8:9]
	v_lshl_add_u64 v[114:115], v[134:135], 1, v[114:115]
	s_mov_b64 s[26:27], -1
	v_mul_f32_e32 v116, v131, v163
	v_pk_mul_f32 v[112:113], v[112:113], v[116:117] op_sel_hi:[1,0]
	v_pk_mul_f32 v[110:111], v[110:111], v[116:117] op_sel_hi:[1,0]
	v_pk_mul_f32 v[120:121], v[108:109], v[116:117] op_sel_hi:[1,0]
	v_pk_mul_f32 v[108:109], v[106:107], v[116:117] op_sel_hi:[1,0]
	v_cvt_pk_bf16_f32 v106, v110, v111
	v_cvt_pk_bf16_f32 v107, v112, v113
	v_cvt_pk_bf16_f32 v108, v108, v109
	v_cvt_pk_bf16_f32 v109, v120, v121
	s_cbranch_vccnz .LBB0_104
	s_mov_b64 s[26:27], 0
	global_store_dwordx4 v[114:115], v[106:109], off

; __device__ __forceinline__ unsigned cvt_pk_bf16(float lo, float hi) { f32x2 v = {lo, hi}; bf16x2_t b = __builtin_convertvector(v, bf16x2_t); return __builtin_bit_cast(unsigned, b); }
;     __device__ __forceinline__ void operator()(const f32x4 (&acc)[2][2][4][2], const Unit& u, int wr, int wc, int fr, int fq) const {
;     ...
;             for (int m = 0; m < 4; ++m) { const int r = row0 + ai * HALF + m * 16; const float s = rs ? rs[r] * cs : cs; bf16_t* rowp = Z + (size_t)r * ldc + col0;
;                 const int seq = r >> sshift, pos = r & ((1 << sshift) - 1), tile = pos >> 6, kv = pos & 63;
; #pragma unroll
;                 for (int bj = 0; bj < 2; ++bj) { const f32x4 v0 = acc[ai][bj][m][0] * s, v1 = acc[ai][bj][m][1] * s; u32x4 w;
;                     w.x = cvt_pk_bf16(v0[0], v0[1]); w.y = cvt_pk_bf16(v0[2], v0[3]); w.z = cvt_pk_bf16(v1[0], v1[1]); w.w = cvt_pk_bf16(v1[2], v1[3]);
.LBB0_110:
	v_or_b32_e32 v102, 32, v130
	v_ashrrev_i32_e32 v103, 31, v102
	v_mov_b64_e32 v[98:99], s[70:71]
	v_mad_i64_i32 v[98:99], s[26:27], v102, s35, v[98:99]
	s_and_b64 vcc, exec, s[8:9]
	v_lshl_add_u64 v[98:99], v[134:135], 1, v[98:99]
	s_mov_b64 s[26:27], -1
	v_mul_f32_e32 v100, v131, v164
	v_pk_mul_f32 v[96:97], v[96:97], v[100:101] op_sel_hi:[1,0]
	v_pk_mul_f32 v[94:95], v[94:95], v[100:101] op_sel_hi:[1,0]
	v_pk_mul_f32 v[104:105], v[92:93], v[100:101] op_sel_hi:[1,0]
	v_pk_mul_f32 v[92:93], v[90:91], v[100:101] op_sel_hi:[1,0]
	v_cvt_pk_bf16_f32 v90, v94, v95
	v_cvt_pk_bf16_f32 v91, v96, v97
	v_cvt_pk_bf16_f32 v92, v92, v93
	v_cvt_pk_bf16_f32 v93, v104, v105
	s_cbranch_vccnz .LBB0_112
	s_mov_b64 s[26:27], 0
	global_store_dwordx4 v[98:99], v[90:93], off

; __device__ __forceinline__ unsigned cvt_pk_bf16(float lo, float hi) { f32x2 v = {lo, hi}; bf16x2_t b = __builtin_convertvector(v, bf16x2_t); return __builtin_bit_cast(unsigned, b); }
;     __device__ __forceinline__ void operator()(const f32x4 (&acc)[2][2][4][2], const Unit& u, int wr, int wc, int fr, int fq) const {
;     ...
;             for (int m = 0; m < 4; ++m) { const int r = row0 + ai * HALF + m * 16; const float s = rs ? rs[r] * cs : cs; bf16_t* rowp = Z + (size_t)r * ldc + col0;
;                 const int seq = r >> sshift, pos = r & ((1 << sshift) - 1), tile = pos >> 6, kv = pos & 63;
; #pragma unroll
;                 for (int bj = 0; bj < 2; ++bj) { const f32x4 v0 = acc[ai][bj][m][0] * s, v1 = acc[ai][bj][m][1] * s; u32x4 w;
;                     w.x = cvt_pk_bf16(v0[0], v0[1]); w.y = cvt_pk_bf16(v0[2], v0[3]); w.z = cvt_pk_bf16(v1[0], v1[1]); w.w = cvt_pk_bf16(v1[2], v1[3]);
.LBB0_118:
	v_or_b32_e32 v86, 48, v130
	v_ashrrev_i32_e32 v87, 31, v86
	v_mov_b64_e32 v[82:83], s[70:71]
	v_mad_i64_i32 v[82:83], s[26:27], v86, s35, v[82:83]
	s_and_b64 vcc, exec, s[8:9]
	v_lshl_add_u64 v[82:83], v[134:135], 1, v[82:83]
	s_mov_b64 s[26:27], -1
	v_mul_f32_e32 v84, v131, v165
	v_pk_mul_f32 v[80:81], v[80:81], v[84:85] op_sel_hi:[1,0]
	v_pk_mul_f32 v[78:79], v[78:79], v[84:85] op_sel_hi:[1,0]
	v_pk_mul_f32 v[88:89], v[76:77], v[84:85] op_sel_hi:[1,0]
	v_pk_mul_f32 v[76:77], v[74:75], v[84:85] op_sel_hi:[1,0]
	v_cvt_pk_bf16_f32 v74, v78, v79
	v_cvt_pk_bf16_f32 v75, v80, v81
	v_cvt_pk_bf16_f32 v76, v76, v77
	v_cvt_pk_bf16_f32 v77, v88, v89
	s_cbranch_vccnz .LBB0_120
	s_mov_b64 s[26:27], 0
	global_store_dwordx4 v[82:83], v[74:77], off
